# one static s_setprio 1 for waves 0-3 at kernel entry (no per-section flips)
# baseline (speedup 1.0000x reference)
; #define LAS __attribute__((address_space(3)))
; __global__ void __launch_bounds__(512, 2) mk_fwd(Args args) {
;     ...
;     const int G = gridDim.x, bx = blockIdx.x;
;     const int vcu = (G % 8 == 0) ? (bx % 8) * (G / 8) + bx / 8 : bx;
;     const int NGW = G * 8;
;     volatile LAS unsigned* MISC = (volatile LAS unsigned*)(lds + RING_BYTES + 1024);
;     if (threadIdx.x == 0) { MISC[0] = 0u; MISC[1] = 0u; }
_Z6mk_fwd4Args:
	s_load_dwordx2 s[88:89], s[0:1], 0xc8
	s_mov_b32 s86, s2
	s_add_u32 s2, s0, 0xc8
	s_addc_u32 s3, s1, 0
	v_writelane_b32 v252, s2, 0
	s_nop 1
	v_writelane_b32 v252, s3, 1
	s_waitcnt lgkmcnt(0)
	s_and_b32 s2, s88, 7
	s_cmp_lg_u32 s2, 0
	v_writelane_b32 v252, s86, 2
	s_cbranch_scc0 .LBB0_577
	v_and_b32_e32 v201, 0x3ff, v0
	s_nop 1
	v_readfirstlane_b32 s3, v201
	s_nop 3
	s_lshr_b32 s3, s3, 6
	s_cmp_lt_u32 s3, 4
	s_cbranch_scc0 .Lprio_done
	s_setprio 1
.Lprio_done:
	v_cmp_eq_u32_e64 s[92:93], 0, v201
	s_and_saveexec_b64 s[2:3], s[92:93]
	s_cbranch_execz .LBB0_3
